# v14 plus GQA and MLA key loops: the MFMA to VALU wait states behind the last S MFMA filled with ten V-transpose LDS reads instead of s_nop
# speedup vs baseline: 1.0021x; 1.0021x over previous
.LBB0_294:
	s_mul_i32 s55, s33, 0x5000
	s_add_i32 s0, s55, 0
	v_add_u32_e32 v68, s0, v122
	s_barrier
	v_add_u32_e32 v48, v68, v125
	v_add_u32_e32 v69, v68, v126
	v_add_u32_e32 v70, v68, v127
	v_add_u32_e32 v68, v68, v128
	v_add_u32_e32 v130, s0, v129
	ds_read_b128 v[192:195], v48
	ds_read_b128 v[196:199], v69
	ds_read_b128 v[200:203], v70
	ds_read_b128 v[208:211], v68
	ds_read_b128 v[98:101], v48 offset:4096
	ds_read_b128 v[102:105], v69 offset:4096
	ds_read_b128 v[106:109], v70 offset:4096
	ds_read_b128 v[132:135], v68 offset:4096
	s_waitcnt lgkmcnt(7)
	v_mfma_f32_32x32x16_bf16 v[48:63], v[192:195], v[82:85], v[32:47]
	s_waitcnt lgkmcnt(6)
	v_mfma_f32_32x32x16_bf16 v[48:63], v[196:199], v[86:89], v[48:63]
	s_waitcnt lgkmcnt(5)
	v_mfma_f32_32x32x16_bf16 v[48:63], v[200:203], v[90:93], v[48:63]
	s_waitcnt lgkmcnt(4)
	v_mfma_f32_32x32x16_bf16 v[48:63], v[208:211], v[94:97], v[48:63]
	s_waitcnt lgkmcnt(3)
	v_mfma_f32_32x32x16_bf16 v[64:79], v[98:101], v[82:85], v[32:47]
	s_waitcnt lgkmcnt(2)
	v_mfma_f32_32x32x16_bf16 v[64:79], v[102:105], v[86:89], v[64:79]
	ds_read_b64_tr_b16 v[110:111], v130 offset:12288
	ds_read_b64_tr_b16 v[112:113], v130 offset:12800
	ds_read_b64_tr_b16 v[102:103], v130 offset:13312
	ds_read_b64_tr_b16 v[104:105], v130 offset:13824
	s_waitcnt lgkmcnt(5)
	v_mfma_f32_32x32x16_bf16 v[64:79], v[106:109], v[90:93], v[64:79]
	s_nop 1
	v_max_f32_e32 v98, v49, v49
	v_max_f32_e32 v99, v48, v48
	v_max_f32_e32 v98, v99, v98
	v_max3_f32 v98, v98, v50, v51
	v_max3_f32 v98, v98, v52, v53
	v_max3_f32 v98, v98, v54, v55
	v_max3_f32 v98, v98, v56, v57
	s_waitcnt lgkmcnt(4)
	v_mfma_f32_32x32x16_bf16 v[64:79], v[132:135], v[94:97], v[64:79]
	v_max3_f32 v98, v98, v58, v59
	v_max3_f32 v98, v98, v60, v61
	v_max3_f32 v98, v98, v62, v63
	ds_read_b64_tr_b16 v[106:107], v130 offset:14336
	ds_read_b64_tr_b16 v[108:109], v130 offset:14848
	ds_read_b64_tr_b16 v[212:213], v130 offset:16384
	ds_read_b64_tr_b16 v[214:215], v130 offset:16896
	ds_read_b64_tr_b16 v[224:225], v130 offset:17408
	ds_read_b64_tr_b16 v[226:227], v130 offset:17920
	ds_read_b64_tr_b16 v[228:229], v130 offset:18432
	ds_read_b64_tr_b16 v[230:231], v130 offset:18944
	ds_read_b64_tr_b16 v[232:233], v130 offset:19456
	ds_read_b64_tr_b16 v[234:235], v130 offset:19968
	v_max3_f32 v98, v98, v64, v65
	v_max3_f32 v98, v98, v66, v67
	v_max3_f32 v98, v98, v68, v69
	v_max3_f32 v98, v98, v70, v71
	v_max3_f32 v98, v98, v72, v73
	v_max3_f32 v98, v98, v74, v75
	v_max3_f32 v98, v98, v76, v77
	v_max3_f32 v131, v98, v78, v79
	s_waitcnt lgkmcnt(10)
	ds_read_b64_tr_b16 v[98:99], v130 offset:15360
	ds_read_b64_tr_b16 v[100:101], v130 offset:15872
	v_cmp_lt_f32_e32 vcc, s72, v131
	s_cbranch_vccz .LBB0_298
	ds_bpermute_b32 v132, v219, v131
	s_waitcnt lgkmcnt(0)
	v_max_f32_e32 v132, v132, v132
	v_max_f32_e32 v131, v131, v132
	v_max_f32_e32 v32, v131, v131
	v_max_f32_e32 v32, 0, v32
	v_exp_f32_e64 v33, -v32
	s_and_saveexec_b64 s[44:45], s[40:41]
	ds_write_b32 v123, v33
	s_or_b64 exec, exec, s[44:45]
	s_waitcnt lgkmcnt(0)
	ds_read_b128 v[34:37], v124
	ds_read_b128 v[38:41], v124 offset:32
	ds_read_b128 v[42:45], v124 offset:64
	ds_read_b128 v[132:135], v124 offset:96
	v_pk_add_f32 v[48:49], v[48:49], v[32:33] op_sel_hi:[1,0] neg_lo:[0,1] neg_hi:[0,1]
	v_pk_add_f32 v[64:65], v[64:65], v[32:33] op_sel_hi:[1,0] neg_lo:[0,1] neg_hi:[0,1]
	v_pk_add_f32 v[50:51], v[50:51], v[32:33] op_sel_hi:[1,0] neg_lo:[0,1] neg_hi:[0,1]
	v_pk_add_f32 v[66:67], v[66:67], v[32:33] op_sel_hi:[1,0] neg_lo:[0,1] neg_hi:[0,1]
	v_pk_add_f32 v[52:53], v[52:53], v[32:33] op_sel_hi:[1,0] neg_lo:[0,1] neg_hi:[0,1]
	v_pk_add_f32 v[68:69], v[68:69], v[32:33] op_sel_hi:[1,0] neg_lo:[0,1] neg_hi:[0,1]
	v_pk_add_f32 v[54:55], v[54:55], v[32:33] op_sel_hi:[1,0] neg_lo:[0,1] neg_hi:[0,1]
	v_pk_add_f32 v[70:71], v[70:71], v[32:33] op_sel_hi:[1,0] neg_lo:[0,1] neg_hi:[0,1]
	v_pk_add_f32 v[56:57], v[56:57], v[32:33] op_sel_hi:[1,0] neg_lo:[0,1] neg_hi:[0,1]
	v_pk_add_f32 v[72:73], v[72:73], v[32:33] op_sel_hi:[1,0] neg_lo:[0,1] neg_hi:[0,1]
	v_pk_add_f32 v[58:59], v[58:59], v[32:33] op_sel_hi:[1,0] neg_lo:[0,1] neg_hi:[0,1]
	v_pk_add_f32 v[74:75], v[74:75], v[32:33] op_sel_hi:[1,0] neg_lo:[0,1] neg_hi:[0,1]
	v_pk_add_f32 v[60:61], v[60:61], v[32:33] op_sel_hi:[1,0] neg_lo:[0,1] neg_hi:[0,1]
	v_pk_add_f32 v[76:77], v[76:77], v[32:33] op_sel_hi:[1,0] neg_lo:[0,1] neg_hi:[0,1]
	v_pk_add_f32 v[62:63], v[62:63], v[32:33] op_sel_hi:[1,0] neg_lo:[0,1] neg_hi:[0,1]
	v_pk_add_f32 v[78:79], v[78:79], v[32:33] op_sel_hi:[1,0] neg_lo:[0,1] neg_hi:[0,1]
	v_pk_add_f32 v[136:137], v[114:115], v[32:33]
	v_pk_mul_f32 v[32:33], v[114:115], v[32:33]
	s_waitcnt lgkmcnt(3)
	v_pk_mul_f32 v[0:1], v[0:1], v[34:35]
	v_mov_b32_e32 v137, v33
	v_pk_add_f32 v[46:47], v[136:137], 0 neg_lo:[1,1] neg_hi:[1,1]
	v_pk_mul_f32 v[2:3], v[2:3], v[36:37]
	s_waitcnt lgkmcnt(2)
	v_pk_mul_f32 v[4:5], v[4:5], v[38:39]
	v_pk_mul_f32 v[6:7], v[6:7], v[40:41]
	s_waitcnt lgkmcnt(1)
	v_pk_mul_f32 v[8:9], v[8:9], v[42:43]
	v_pk_mul_f32 v[10:11], v[10:11], v[44:45]
	s_waitcnt lgkmcnt(0)
	v_pk_mul_f32 v[12:13], v[12:13], v[132:133]
	v_pk_mul_f32 v[14:15], v[14:15], v[134:135]
	v_pk_mul_f32 v[30:31], v[30:31], v[134:135]
	v_pk_mul_f32 v[26:27], v[26:27], v[44:45]
	v_pk_mul_f32 v[22:23], v[22:23], v[40:41]
	v_pk_mul_f32 v[18:19], v[18:19], v[36:37]
	v_pk_mul_f32 v[28:29], v[28:29], v[132:133]
	v_pk_mul_f32 v[24:25], v[24:25], v[42:43]
	v_pk_mul_f32 v[20:21], v[20:21], v[38:39]
	v_pk_mul_f32 v[16:17], v[16:17], v[34:35]
	v_mov_b32_e32 v47, v46
	v_mov_b32_e32 v45, v46
	v_mov_b32_e32 v44, v46
	v_mov_b32_e32 v43, v46
	v_mov_b32_e32 v42, v46
	v_mov_b32_e32 v41, v46
	v_mov_b32_e32 v40, v46
	v_mov_b32_e32 v39, v46
	v_mov_b32_e32 v38, v46
	v_mov_b32_e32 v37, v46
	v_mov_b32_e32 v36, v46
	v_mov_b32_e32 v35, v46
	v_mov_b32_e32 v34, v46
	v_mov_b32_e32 v33, v46
	v_mov_b32_e32 v32, v46
	v_mov_b64_e32 v[114:115], v[136:137]

.LBB0_345:
	s_mul_i32 s54, s11, 0x5000
	s_add_i32 s0, s54, 0
	v_add_u32_e32 v68, s0, v132
	s_barrier
	v_add_u32_e32 v69, v68, v136
	v_add_u32_e32 v110, v68, v137
	v_add_u32_e32 v111, v68, v138
	v_add_u32_e32 v112, v68, v139
	v_add_u32_e32 v68, s0, v133
	v_add_u32_e32 v113, v68, v140
	v_add_u32_e32 v118, v68, v141
	v_add_u32_e32 v143, s0, v142
	ds_read_b128 v[190:193], v69
	ds_read_b128 v[194:197], v110
	ds_read_b128 v[198:201], v111
	ds_read_b128 v[208:211], v112
	ds_read_b128 v[212:215], v113 offset:8192
	ds_read_b128 v[222:225], v118 offset:8192
	ds_read_b128 v[226:229], v69 offset:4096
	ds_read_b128 v[230:233], v110 offset:4096
	ds_read_b128 v[234:237], v111 offset:4096
	ds_read_b128 v[238:241], v112 offset:4096
	ds_read_b128 v[242:245], v113 offset:10240
	ds_read_b128 v[246:249], v118 offset:10240
	s_waitcnt lgkmcnt(11)
	v_mfma_f32_32x32x16_bf16 v[48:63], v[190:193], v[82:85], v[16:31]
	s_waitcnt lgkmcnt(10)
	v_mfma_f32_32x32x16_bf16 v[48:63], v[194:197], v[86:89], v[48:63]
	s_waitcnt lgkmcnt(9)
	v_mfma_f32_32x32x16_bf16 v[48:63], v[198:201], v[90:93], v[48:63]
	s_waitcnt lgkmcnt(8)
	v_mfma_f32_32x32x16_bf16 v[48:63], v[208:211], v[94:97], v[48:63]
	s_waitcnt lgkmcnt(7)
	v_mfma_f32_32x32x16_bf16 v[48:63], v[212:215], v[98:101], v[48:63]
	s_waitcnt lgkmcnt(6)
	v_mfma_f32_32x32x16_bf16 v[48:63], v[222:225], v[102:105], v[48:63]
	s_waitcnt lgkmcnt(5)
	v_mfma_f32_32x32x16_bf16 v[64:79], v[226:229], v[82:85], v[16:31]
	s_waitcnt lgkmcnt(4)
	v_mfma_f32_32x32x16_bf16 v[64:79], v[230:233], v[86:89], v[64:79]
	ds_read_b64_tr_b16 v[118:119], v143 offset:12288
	ds_read_b64_tr_b16 v[120:121], v143 offset:12800
	ds_read_b64_tr_b16 v[110:111], v143 offset:13312
	ds_read_b64_tr_b16 v[112:113], v143 offset:13824
	s_waitcnt lgkmcnt(7)
	v_mfma_f32_32x32x16_bf16 v[64:79], v[234:237], v[90:93], v[64:79]
	s_waitcnt lgkmcnt(6)
	v_mfma_f32_32x32x16_bf16 v[64:79], v[238:241], v[94:97], v[64:79]
	v_max_f32_e32 v106, v49, v49
	v_max_f32_e32 v107, v48, v48
	v_max_f32_e32 v106, v107, v106
	v_max3_f32 v106, v106, v50, v51
	v_max3_f32 v106, v106, v52, v53
	v_max3_f32 v106, v106, v54, v55
	v_max3_f32 v106, v106, v56, v57
	s_waitcnt lgkmcnt(5)
	v_mfma_f32_32x32x16_bf16 v[64:79], v[242:245], v[98:101], v[64:79]
	v_max3_f32 v106, v106, v58, v59
	v_max3_f32 v106, v106, v60, v61
	v_max3_f32 v106, v106, v62, v63
	s_waitcnt lgkmcnt(4)
	v_mfma_f32_32x32x16_bf16 v[64:79], v[246:249], v[102:105], v[64:79]
	ds_read_b64_tr_b16 v[114:115], v143 offset:14336
	ds_read_b64_tr_b16 v[116:117], v143 offset:14848
	ds_read_b64_tr_b16 v[190:191], v143 offset:16384
	ds_read_b64_tr_b16 v[192:193], v143 offset:16896
	ds_read_b64_tr_b16 v[194:195], v143 offset:17408
	ds_read_b64_tr_b16 v[196:197], v143 offset:17920
	ds_read_b64_tr_b16 v[198:199], v143 offset:18432
	ds_read_b64_tr_b16 v[200:201], v143 offset:18944
	ds_read_b64_tr_b16 v[208:209], v143 offset:19456
	ds_read_b64_tr_b16 v[210:211], v143 offset:19968
	s_nop 1
	v_max3_f32 v106, v106, v64, v65
	v_max3_f32 v106, v106, v66, v67
	v_max3_f32 v106, v106, v68, v69
	v_max3_f32 v106, v106, v70, v71
	v_max3_f32 v106, v106, v72, v73
	v_max3_f32 v106, v106, v74, v75
	v_max3_f32 v106, v106, v76, v77
	v_max3_f32 v144, v106, v78, v79
	s_waitcnt lgkmcnt(10)
	ds_read_b64_tr_b16 v[106:107], v143 offset:15360
	ds_read_b64_tr_b16 v[108:109], v143 offset:15872
	v_cmp_lt_f32_e32 vcc, s72, v144
	s_cbranch_vccz .LBB0_349
	ds_bpermute_b32 v145, v219, v144
	s_waitcnt lgkmcnt(0)
	v_max_f32_e32 v145, v145, v145
	v_max_f32_e32 v144, v144, v145
	v_max_f32_e32 v16, v144, v144
	v_max_f32_e32 v16, 0, v16
	v_exp_f32_e64 v17, -v16
	s_and_saveexec_b64 s[28:29], s[40:41]
	ds_write_b32 v134, v17
	s_or_b64 exec, exec, s[28:29]
	s_waitcnt lgkmcnt(0)
	ds_read_b128 v[18:21], v135
	ds_read_b128 v[22:25], v135 offset:32
	ds_read_b128 v[26:29], v135 offset:64
	ds_read_b128 v[144:147], v135 offset:96
	v_pk_add_f32 v[48:49], v[48:49], v[16:17] op_sel_hi:[1,0] neg_lo:[0,1] neg_hi:[0,1]
	v_pk_add_f32 v[64:65], v[64:65], v[16:17] op_sel_hi:[1,0] neg_lo:[0,1] neg_hi:[0,1]
	v_pk_add_f32 v[50:51], v[50:51], v[16:17] op_sel_hi:[1,0] neg_lo:[0,1] neg_hi:[0,1]
	v_pk_add_f32 v[66:67], v[66:67], v[16:17] op_sel_hi:[1,0] neg_lo:[0,1] neg_hi:[0,1]
	v_pk_add_f32 v[52:53], v[52:53], v[16:17] op_sel_hi:[1,0] neg_lo:[0,1] neg_hi:[0,1]
	v_pk_add_f32 v[68:69], v[68:69], v[16:17] op_sel_hi:[1,0] neg_lo:[0,1] neg_hi:[0,1]
	v_pk_add_f32 v[54:55], v[54:55], v[16:17] op_sel_hi:[1,0] neg_lo:[0,1] neg_hi:[0,1]
	v_pk_add_f32 v[70:71], v[70:71], v[16:17] op_sel_hi:[1,0] neg_lo:[0,1] neg_hi:[0,1]
	v_pk_add_f32 v[56:57], v[56:57], v[16:17] op_sel_hi:[1,0] neg_lo:[0,1] neg_hi:[0,1]
	v_pk_add_f32 v[72:73], v[72:73], v[16:17] op_sel_hi:[1,0] neg_lo:[0,1] neg_hi:[0,1]
	v_pk_add_f32 v[58:59], v[58:59], v[16:17] op_sel_hi:[1,0] neg_lo:[0,1] neg_hi:[0,1]
	v_pk_add_f32 v[74:75], v[74:75], v[16:17] op_sel_hi:[1,0] neg_lo:[0,1] neg_hi:[0,1]
	v_pk_add_f32 v[60:61], v[60:61], v[16:17] op_sel_hi:[1,0] neg_lo:[0,1] neg_hi:[0,1]
	v_pk_add_f32 v[76:77], v[76:77], v[16:17] op_sel_hi:[1,0] neg_lo:[0,1] neg_hi:[0,1]
	v_pk_add_f32 v[62:63], v[62:63], v[16:17] op_sel_hi:[1,0] neg_lo:[0,1] neg_hi:[0,1]
	v_pk_add_f32 v[78:79], v[78:79], v[16:17] op_sel_hi:[1,0] neg_lo:[0,1] neg_hi:[0,1]
	v_pk_add_f32 v[152:153], v[122:123], v[16:17]
	v_pk_mul_f32 v[16:17], v[122:123], v[16:17]
	s_waitcnt lgkmcnt(3)
	v_pk_mul_f32 v[0:1], v[0:1], v[18:19]
	v_mov_b32_e32 v153, v17
	v_pk_add_f32 v[30:31], v[152:153], 0 neg_lo:[1,1] neg_hi:[1,1]
	v_pk_mul_f32 v[2:3], v[2:3], v[20:21]
	s_waitcnt lgkmcnt(2)
	v_pk_mul_f32 v[4:5], v[4:5], v[22:23]
	v_pk_mul_f32 v[6:7], v[6:7], v[24:25]
	s_waitcnt lgkmcnt(1)
	v_pk_mul_f32 v[8:9], v[8:9], v[26:27]
	v_pk_mul_f32 v[10:11], v[10:11], v[28:29]
	s_waitcnt lgkmcnt(0)
	v_pk_mul_f32 v[12:13], v[12:13], v[144:145]
	v_pk_mul_f32 v[14:15], v[14:15], v[146:147]
	v_pk_mul_f32 v[46:47], v[46:47], v[146:147]
	v_pk_mul_f32 v[42:43], v[42:43], v[28:29]
	v_pk_mul_f32 v[38:39], v[38:39], v[24:25]
	v_pk_mul_f32 v[34:35], v[34:35], v[20:21]
	v_pk_mul_f32 v[44:45], v[44:45], v[144:145]
	v_pk_mul_f32 v[40:41], v[40:41], v[26:27]
	v_pk_mul_f32 v[36:37], v[36:37], v[22:23]
	v_pk_mul_f32 v[32:33], v[32:33], v[18:19]
	v_mov_b32_e32 v31, v30
	v_mov_b32_e32 v29, v30
	v_mov_b32_e32 v28, v30
	v_mov_b32_e32 v27, v30
	v_mov_b32_e32 v26, v30
	v_mov_b32_e32 v25, v30
	v_mov_b32_e32 v24, v30
	v_mov_b32_e32 v23, v30
	v_mov_b32_e32 v22, v30
	v_mov_b32_e32 v21, v30
	v_mov_b32_e32 v20, v30
	v_mov_b32_e32 v19, v30
	v_mov_b32_e32 v18, v30
	v_mov_b32_e32 v17, v30
	v_mov_b32_e32 v16, v30
	v_mov_b64_e32 v[122:123], v[152:153]
